# P12 prompt row pass software-pipelined (next row pair's loads in flight during compute, two register sets)
# baseline (speedup 1.0000x reference)
; template <bool DRYR = false>
; __device__ __forceinline__ void row_pass2(const Args& a, int row_lo, int row_hi, int gw, int NGW, int lane) {
;     ...
;     for (int r0 = row_lo + 2 * gw; r0 < row_hi; r0 += 2 * NGW) {
;         f32x4 xv[2][4]; u32x2 fv[2][4]; float rs[2];
; #pragma unroll
;         for (int r = 0; r < 2; ++r) { const int row = (r0 + r < row_hi) ? r0 + r : r0; rs[r] = rss[row];
;             const f32x4* xo = (const f32x4*)(XO + (size_t)row * DM) + lane; const u32x2* fr = (const u32x2*)(F + (size_t)row * DM) + lane;
; #pragma unroll
;             for (int j = 0; j < 4; ++j) { xv[r][j] = xo[64 * j]; fv[r][j] = fr[64 * j]; } }
.LBB0_1413:
	s_and_b64 vcc, exec, s[10:11]
	s_cbranch_vccz .LBB0_1419
	s_lshl_b32 s0, s81, 1
	s_addk_i32 s0, 0xfe00
	s_cmpk_gt_i32 s0, 0x3fff
	s_cbranch_scc1 .LBB0_1419
	s_waitcnt vmcnt(0)
	v_mov_b32_e32 v145, 0
	v_readlane_b32 s20, v252, 1
	v_readlane_b32 s21, v252, 2
	v_readlane_b32 s14, v252, 13
	v_readlane_b32 s15, v252, 14
	v_lshlrev_b32_e32 v146, 3, v176
	v_add_u32_e32 v147, 0x1000, v144
	v_mov_b32_e32 v116, 0x358637bd
	s_lshl_b32 s1, s58, 4
	s_add_i32 s4, s1, 0xfffffe00
	s_ashr_i32 s1, s0, 31
	s_lshl_b64 s[10:11], s[0:1], 12
	global_load_dwordx4 v[84:87], v144, s[14:15]
	global_load_dwordx4 v[88:91], v144, s[14:15] offset:1024
	global_load_dwordx4 v[92:95], v144, s[14:15] offset:2048
	global_load_dwordx4 v[96:99], v144, s[14:15] offset:3072
	s_add_u32 s20, s20, s10
	s_addc_u32 s21, s21, s11
	s_add_u32 s22, s52, s10
	s_addc_u32 s23, s53, s11
	s_lshl_b64 s[10:11], s[0:1], 11
	s_add_u32 s24, s54, s10
	s_addc_u32 s25, s55, s11
	s_add_u32 s26, s24, 0xbc00000
	s_addc_u32 s27, s25, 0
	s_add_u32 s24, s24, 0xde00000
	s_addc_u32 s25, s25, 0
	s_lshl_b64 s[10:11], s[0:1], 2
	s_add_u32 s16, s54, s10
	s_addc_u32 s17, s55, s11
	s_add_u32 s18, s16, 0x2291000
	s_addc_u32 s19, s17, 0
	s_add_u32 s16, s16, 0x2280000
	s_addc_u32 s17, s17, 0
	s_lshl_b32 s98, s4, 12
	s_lshl_b32 s99, s4, 11
	s_lshl_b32 s100, s4, 2
	s_mov_b32 s3, 0x800000
	global_load_dwordx2 v[80:81], v145, s[16:17]
	global_load_dwordx2 v[82:83], v145, s[18:19]
	global_load_dwordx2 v[48:49], v146, s[24:25] nt
	global_load_dwordx2 v[50:51], v146, s[24:25] offset:512 nt
	global_load_dwordx2 v[52:53], v146, s[24:25] offset:1024 nt
	global_load_dwordx2 v[54:55], v146, s[24:25] offset:1536 nt
	global_load_dwordx4 v[16:19], v144, s[20:21] nt
	global_load_dwordx4 v[20:23], v144, s[20:21] offset:1024 nt
	global_load_dwordx4 v[24:27], v144, s[20:21] offset:2048 nt
	global_load_dwordx4 v[28:31], v144, s[20:21] offset:3072 nt
	global_load_dwordx2 v[64:65], v146, s[26:27] nt
	global_load_dwordx2 v[66:67], v146, s[26:27] offset:512 nt
	global_load_dwordx2 v[68:69], v146, s[26:27] offset:1024 nt
	global_load_dwordx2 v[70:71], v146, s[26:27] offset:1536 nt
	global_load_dwordx2 v[56:57], v146, s[24:25] offset:2048 nt
	global_load_dwordx2 v[58:59], v146, s[24:25] offset:2560 nt
	global_load_dwordx2 v[60:61], v146, s[24:25] offset:3072 nt
	global_load_dwordx2 v[62:63], v146, s[24:25] offset:3584 nt
	global_load_dwordx4 v[32:35], v147, s[20:21] nt
	global_load_dwordx4 v[36:39], v147, s[20:21] offset:1024 nt
	global_load_dwordx4 v[40:43], v147, s[20:21] offset:2048 nt
	global_load_dwordx4 v[44:47], v147, s[20:21] offset:3072 nt
	global_load_dwordx2 v[72:73], v146, s[26:27] offset:2048 nt
	global_load_dwordx2 v[74:75], v146, s[26:27] offset:2560 nt
	global_load_dwordx2 v[76:77], v146, s[26:27] offset:3072 nt
	global_load_dwordx2 v[78:79], v146, s[26:27] offset:3584 nt
	s_add_i32 s0, s0, s4
	s_add_u32 s20, s20, s98
	s_addc_u32 s21, s21, 0
	s_add_u32 s24, s24, s99
	s_addc_u32 s25, s25, 0
	s_add_u32 s26, s26, s99
	s_addc_u32 s27, s27, 0
	s_add_u32 s16, s16, s100
	s_addc_u32 s17, s17, 0
	s_add_u32 s18, s18, s100
	s_addc_u32 s19, s19, 0
.Lxo_half0:
	s_mov_b32 s101, 0
	s_cmpk_gt_i32 s0, 0x3fff
	s_cbranch_scc1 .Lxo_nonext0
	global_load_dwordx2 v[180:181], v145, s[16:17]
	global_load_dwordx2 v[182:183], v145, s[18:19]
	global_load_dwordx2 v[184:185], v146, s[24:25] nt
	global_load_dwordx2 v[186:187], v146, s[24:25] offset:512 nt
	global_load_dwordx2 v[188:189], v146, s[24:25] offset:1024 nt
	global_load_dwordx2 v[190:191], v146, s[24:25] offset:1536 nt
	global_load_dwordx4 v[200:203], v144, s[20:21] nt
	global_load_dwordx4 v[204:207], v144, s[20:21] offset:1024 nt
	global_load_dwordx4 v[208:211], v144, s[20:21] offset:2048 nt
	global_load_dwordx4 v[212:215], v144, s[20:21] offset:3072 nt
	global_load_dwordx2 v[232:233], v146, s[26:27] nt
	global_load_dwordx2 v[234:235], v146, s[26:27] offset:512 nt
	global_load_dwordx2 v[236:237], v146, s[26:27] offset:1024 nt
	global_load_dwordx2 v[238:239], v146, s[26:27] offset:1536 nt
	global_load_dwordx2 v[192:193], v146, s[24:25] offset:2048 nt
	global_load_dwordx2 v[194:195], v146, s[24:25] offset:2560 nt
	global_load_dwordx2 v[196:197], v146, s[24:25] offset:3072 nt
	global_load_dwordx2 v[198:199], v146, s[24:25] offset:3584 nt
	global_load_dwordx4 v[216:219], v147, s[20:21] nt
	global_load_dwordx4 v[220:223], v147, s[20:21] offset:1024 nt
	global_load_dwordx4 v[224:227], v147, s[20:21] offset:2048 nt
	global_load_dwordx4 v[228:231], v147, s[20:21] offset:3072 nt
	global_load_dwordx2 v[240:241], v146, s[26:27] offset:2048 nt
	global_load_dwordx2 v[242:243], v146, s[26:27] offset:2560 nt
	global_load_dwordx2 v[244:245], v146, s[26:27] offset:3072 nt
	global_load_dwordx2 v[246:247], v146, s[26:27] offset:3584 nt
	s_add_i32 s0, s0, s4
	s_add_u32 s20, s20, s98
	s_addc_u32 s21, s21, 0
	s_add_u32 s24, s24, s99
	s_addc_u32 s25, s25, 0
	s_add_u32 s26, s26, s99
	s_addc_u32 s27, s27, 0
	s_add_u32 s16, s16, s100
	s_addc_u32 s17, s17, 0
	s_add_u32 s18, s18, s100
	s_addc_u32 s19, s19, 0
	s_mov_b32 s101, 1
	s_waitcnt vmcnt(38)
	s_branch .Lxo_rowA0
.Lxo_nonext0:
	s_waitcnt vmcnt(12)
; __device__ __forceinline__ f32x4 up4(u32x2 w) { return (f32x4){bf_lo(w.x), bf_hi(w.x), bf_lo(w.y), bf_hi(w.y)}; }
; template <bool DRYR = false>
; __device__ __forceinline__ void row_pass2(const Args& a, int row_lo, int row_hi, int gw, int NGW, int lane) {
;     ...
;         for (int r = 0; r < 2; ++r) { const int row = r0 + r; if (row >= row_hi) break;
;             const float rstd = rsqrtf(rs[r] * (1.f / DM) + EPS); f32x4* xo = (f32x4*)(XO + (size_t)row * DM) + lane;
; #pragma unroll
;             for (int j = 0; j < 4; ++j) { const f32x4 o = xv[r][j] + up4(fv[r][j]) * rstd * gp[j]; if (!DRYR || o[0] == 123.456f) xo[64 * j] = o; } }
.Lxo_rowA0:
	v_fmamk_f32 v104, v80, 0x3a800000, v116
	v_mul_f32_e32 v105, 0x4b800000, v104
	v_cmp_gt_f32_e32 vcc, s3, v104
	s_nop 1
	v_cndmask_b32_e32 v104, v104, v105, vcc
	v_rsq_f32_e32 v104, v104
	s_nop 0
	v_mul_f32_e32 v105, 0x45800000, v104
	v_cndmask_b32_e32 v104, v104, v105, vcc
	v_fmamk_f32 v106, v82, 0x3a800000, v116
	v_mul_f32_e32 v107, 0x4b800000, v106
	v_cmp_gt_f32_e32 vcc, s3, v106
	s_nop 1
	v_cndmask_b32_e32 v106, v106, v107, vcc
	v_rsq_f32_e32 v106, v106
	s_nop 0
	v_mul_f32_e32 v107, 0x45800000, v106
	v_cndmask_b32_e32 v106, v106, v107, vcc
	v_lshlrev_b32_e32 v120, 16, v48
	v_and_b32_e32 v121, 0xffff0000, v48
	v_lshlrev_b32_e32 v122, 16, v49
	v_and_b32_e32 v123, 0xffff0000, v49
	v_lshlrev_b32_e32 v150, 16, v64
	v_and_b32_e32 v151, 0xffff0000, v64
	v_lshlrev_b32_e32 v152, 16, v65
	v_and_b32_e32 v153, 0xffff0000, v65
	v_pk_mul_f32 v[120:121], v[104:105], v[120:121] op_sel_hi:[0,1]
	v_pk_mul_f32 v[122:123], v[104:105], v[122:123] op_sel_hi:[0,1]
	v_pk_mul_f32 v[150:151], v[106:107], v[150:151] op_sel_hi:[0,1]
	v_pk_mul_f32 v[152:153], v[106:107], v[152:153] op_sel_hi:[0,1]
	v_pk_fma_f32 v[16:17], v[84:85], v[120:121], v[16:17]
	v_pk_fma_f32 v[18:19], v[86:87], v[122:123], v[18:19]
	v_pk_fma_f32 v[16:17], v[0:1], v[150:151], v[16:17]
	v_pk_fma_f32 v[18:19], v[2:3], v[152:153], v[18:19]
	v_lshlrev_b32_e32 v124, 16, v50
	v_and_b32_e32 v125, 0xffff0000, v50
	v_lshlrev_b32_e32 v126, 16, v51
	v_and_b32_e32 v127, 0xffff0000, v51
	v_lshlrev_b32_e32 v154, 16, v66
	v_and_b32_e32 v155, 0xffff0000, v66
	v_lshlrev_b32_e32 v156, 16, v67
	v_and_b32_e32 v157, 0xffff0000, v67
	v_pk_mul_f32 v[124:125], v[104:105], v[124:125] op_sel_hi:[0,1]
	v_pk_mul_f32 v[126:127], v[104:105], v[126:127] op_sel_hi:[0,1]
	v_pk_mul_f32 v[154:155], v[106:107], v[154:155] op_sel_hi:[0,1]
	v_pk_mul_f32 v[156:157], v[106:107], v[156:157] op_sel_hi:[0,1]
	v_pk_fma_f32 v[20:21], v[88:89], v[124:125], v[20:21]
	v_pk_fma_f32 v[22:23], v[90:91], v[126:127], v[22:23]
	v_pk_fma_f32 v[20:21], v[4:5], v[154:155], v[20:21]
	v_pk_fma_f32 v[22:23], v[6:7], v[156:157], v[22:23]
	v_lshlrev_b32_e32 v128, 16, v52
	v_and_b32_e32 v129, 0xffff0000, v52
	v_lshlrev_b32_e32 v130, 16, v53
	v_and_b32_e32 v131, 0xffff0000, v53
	v_lshlrev_b32_e32 v158, 16, v68
	v_and_b32_e32 v159, 0xffff0000, v68
	v_lshlrev_b32_e32 v160, 16, v69
	v_and_b32_e32 v161, 0xffff0000, v69
	v_pk_mul_f32 v[128:129], v[104:105], v[128:129] op_sel_hi:[0,1]
	v_pk_mul_f32 v[130:131], v[104:105], v[130:131] op_sel_hi:[0,1]
	v_pk_mul_f32 v[158:159], v[106:107], v[158:159] op_sel_hi:[0,1]
	v_pk_mul_f32 v[160:161], v[106:107], v[160:161] op_sel_hi:[0,1]
	v_pk_fma_f32 v[24:25], v[92:93], v[128:129], v[24:25]
	v_pk_fma_f32 v[26:27], v[94:95], v[130:131], v[26:27]
	v_pk_fma_f32 v[24:25], v[8:9], v[158:159], v[24:25]
	v_pk_fma_f32 v[26:27], v[10:11], v[160:161], v[26:27]
	v_lshlrev_b32_e32 v132, 16, v54
	v_and_b32_e32 v133, 0xffff0000, v54
	v_lshlrev_b32_e32 v134, 16, v55
	v_and_b32_e32 v135, 0xffff0000, v55
	v_lshlrev_b32_e32 v162, 16, v70
	v_and_b32_e32 v163, 0xffff0000, v70
	v_lshlrev_b32_e32 v164, 16, v71
	v_and_b32_e32 v165, 0xffff0000, v71
	v_pk_mul_f32 v[132:133], v[104:105], v[132:133] op_sel_hi:[0,1]
	v_pk_mul_f32 v[134:135], v[104:105], v[134:135] op_sel_hi:[0,1]
	v_pk_mul_f32 v[162:163], v[106:107], v[162:163] op_sel_hi:[0,1]
	v_pk_mul_f32 v[164:165], v[106:107], v[164:165] op_sel_hi:[0,1]
	v_pk_fma_f32 v[28:29], v[96:97], v[132:133], v[28:29]
	v_pk_fma_f32 v[30:31], v[98:99], v[134:135], v[30:31]
	v_pk_fma_f32 v[28:29], v[12:13], v[162:163], v[28:29]
	v_pk_fma_f32 v[30:31], v[14:15], v[164:165], v[30:31]
	global_store_dwordx4 v144, v[16:19], s[22:23] nt
	global_store_dwordx4 v144, v[20:23], s[22:23] offset:1024 nt
	global_store_dwordx4 v144, v[24:27], s[22:23] offset:2048 nt
	global_store_dwordx4 v144, v[28:31], s[22:23] offset:3072 nt
	s_cmp_lg_u32 s101, 0
	s_cbranch_scc1 .Lxo_wB0
	s_waitcnt vmcnt(4)
	s_branch .Lxo_rowB0
.Lxo_wB0:
	s_waitcnt vmcnt(30)
; __device__ __forceinline__ f32x4 up4(u32x2 w) { return (f32x4){bf_lo(w.x), bf_hi(w.x), bf_lo(w.y), bf_hi(w.y)}; }
; template <bool DRYR = false>
; __device__ __forceinline__ void row_pass2(const Args& a, int row_lo, int row_hi, int gw, int NGW, int lane) {
;     ...
;     for (int r0 = row_lo + 2 * gw; r0 < row_hi; r0 += 2 * NGW) {
;         f32x4 xv[2][4]; u32x2 fv[2][4]; float rs[2];
; #pragma unroll
;         for (int r = 0; r < 2; ++r) { const int row = (r0 + r < row_hi) ? r0 + r : r0; rs[r] = rss[row];
;             const f32x4* xo = (const f32x4*)(XO + (size_t)row * DM) + lane; const u32x2* fr = (const u32x2*)(F + (size_t)row * DM) + lane;
; #pragma unroll
;             for (int j = 0; j < 4; ++j) { xv[r][j] = xo[64 * j]; fv[r][j] = fr[64 * j]; } }
;     ...
;         for (int r = 0; r < 2; ++r) { const int row = r0 + r; if (row >= row_hi) break;
;             const float rstd = rsqrtf(rs[r] * (1.f / DM) + EPS); f32x4* xo = (f32x4*)(XO + (size_t)row * DM) + lane;
; #pragma unroll
;             for (int j = 0; j < 4; ++j) { const f32x4 o = xv[r][j] + up4(fv[r][j]) * rstd * gp[j]; if (!DRYR || o[0] == 123.456f) xo[64 * j] = o; } }
.Lxo_rowB0:
	v_fmamk_f32 v104, v81, 0x3a800000, v116
	v_mul_f32_e32 v105, 0x4b800000, v104
	v_cmp_gt_f32_e32 vcc, s3, v104
	s_nop 1
	v_cndmask_b32_e32 v104, v104, v105, vcc
	v_rsq_f32_e32 v104, v104
	s_nop 0
	v_mul_f32_e32 v105, 0x45800000, v104
	v_cndmask_b32_e32 v104, v104, v105, vcc
	v_fmamk_f32 v106, v83, 0x3a800000, v116
	v_mul_f32_e32 v107, 0x4b800000, v106
	v_cmp_gt_f32_e32 vcc, s3, v106
	s_nop 1
	v_cndmask_b32_e32 v106, v106, v107, vcc
	v_rsq_f32_e32 v106, v106
	s_nop 0
	v_mul_f32_e32 v107, 0x45800000, v106
	v_cndmask_b32_e32 v106, v106, v107, vcc
	v_lshlrev_b32_e32 v120, 16, v56
	v_and_b32_e32 v121, 0xffff0000, v56
	v_lshlrev_b32_e32 v122, 16, v57
	v_and_b32_e32 v123, 0xffff0000, v57
	v_lshlrev_b32_e32 v150, 16, v72
	v_and_b32_e32 v151, 0xffff0000, v72
	v_lshlrev_b32_e32 v152, 16, v73
	v_and_b32_e32 v153, 0xffff0000, v73
	v_pk_mul_f32 v[120:121], v[104:105], v[120:121] op_sel_hi:[0,1]
	v_pk_mul_f32 v[122:123], v[104:105], v[122:123] op_sel_hi:[0,1]
	v_pk_mul_f32 v[150:151], v[106:107], v[150:151] op_sel_hi:[0,1]
	v_pk_mul_f32 v[152:153], v[106:107], v[152:153] op_sel_hi:[0,1]
	v_pk_fma_f32 v[32:33], v[84:85], v[120:121], v[32:33]
	v_pk_fma_f32 v[34:35], v[86:87], v[122:123], v[34:35]
	v_pk_fma_f32 v[32:33], v[0:1], v[150:151], v[32:33]
	v_pk_fma_f32 v[34:35], v[2:3], v[152:153], v[34:35]
	v_lshlrev_b32_e32 v124, 16, v58
	v_and_b32_e32 v125, 0xffff0000, v58
	v_lshlrev_b32_e32 v126, 16, v59
	v_and_b32_e32 v127, 0xffff0000, v59
	v_lshlrev_b32_e32 v154, 16, v74
	v_and_b32_e32 v155, 0xffff0000, v74
	v_lshlrev_b32_e32 v156, 16, v75
	v_and_b32_e32 v157, 0xffff0000, v75
	v_pk_mul_f32 v[124:125], v[104:105], v[124:125] op_sel_hi:[0,1]
	v_pk_mul_f32 v[126:127], v[104:105], v[126:127] op_sel_hi:[0,1]
	v_pk_mul_f32 v[154:155], v[106:107], v[154:155] op_sel_hi:[0,1]
	v_pk_mul_f32 v[156:157], v[106:107], v[156:157] op_sel_hi:[0,1]
	v_pk_fma_f32 v[36:37], v[88:89], v[124:125], v[36:37]
	v_pk_fma_f32 v[38:39], v[90:91], v[126:127], v[38:39]
	v_pk_fma_f32 v[36:37], v[4:5], v[154:155], v[36:37]
	v_pk_fma_f32 v[38:39], v[6:7], v[156:157], v[38:39]
	v_lshlrev_b32_e32 v128, 16, v60
	v_and_b32_e32 v129, 0xffff0000, v60
	v_lshlrev_b32_e32 v130, 16, v61
	v_and_b32_e32 v131, 0xffff0000, v61
	v_lshlrev_b32_e32 v158, 16, v76
	v_and_b32_e32 v159, 0xffff0000, v76
	v_lshlrev_b32_e32 v160, 16, v77
	v_and_b32_e32 v161, 0xffff0000, v77
	v_pk_mul_f32 v[128:129], v[104:105], v[128:129] op_sel_hi:[0,1]
	v_pk_mul_f32 v[130:131], v[104:105], v[130:131] op_sel_hi:[0,1]
	v_pk_mul_f32 v[158:159], v[106:107], v[158:159] op_sel_hi:[0,1]
	v_pk_mul_f32 v[160:161], v[106:107], v[160:161] op_sel_hi:[0,1]
	v_pk_fma_f32 v[40:41], v[92:93], v[128:129], v[40:41]
	v_pk_fma_f32 v[42:43], v[94:95], v[130:131], v[42:43]
	v_pk_fma_f32 v[40:41], v[8:9], v[158:159], v[40:41]
	v_pk_fma_f32 v[42:43], v[10:11], v[160:161], v[42:43]
	v_lshlrev_b32_e32 v132, 16, v62
	v_and_b32_e32 v133, 0xffff0000, v62
	v_lshlrev_b32_e32 v134, 16, v63
	v_and_b32_e32 v135, 0xffff0000, v63
	v_lshlrev_b32_e32 v162, 16, v78
	v_and_b32_e32 v163, 0xffff0000, v78
	v_lshlrev_b32_e32 v164, 16, v79
	v_and_b32_e32 v165, 0xffff0000, v79
	v_pk_mul_f32 v[132:133], v[104:105], v[132:133] op_sel_hi:[0,1]
	v_pk_mul_f32 v[134:135], v[104:105], v[134:135] op_sel_hi:[0,1]
	v_pk_mul_f32 v[162:163], v[106:107], v[162:163] op_sel_hi:[0,1]
	v_pk_mul_f32 v[164:165], v[106:107], v[164:165] op_sel_hi:[0,1]
	v_pk_fma_f32 v[44:45], v[96:97], v[132:133], v[44:45]
	v_pk_fma_f32 v[46:47], v[98:99], v[134:135], v[46:47]
	v_pk_fma_f32 v[44:45], v[12:13], v[162:163], v[44:45]
	v_pk_fma_f32 v[46:47], v[14:15], v[164:165], v[46:47]
	global_store_dwordx4 v147, v[32:35], s[22:23] nt
	global_store_dwordx4 v147, v[36:39], s[22:23] offset:1024 nt
	global_store_dwordx4 v147, v[40:43], s[22:23] offset:2048 nt
	global_store_dwordx4 v147, v[44:47], s[22:23] offset:3072 nt
	s_add_u32 s22, s22, s98
	s_addc_u32 s23, s23, 0
	s_cmp_lg_u32 s101, 0
	s_cbranch_scc0 .Lxo_done
.Lxo_half1:
	s_mov_b32 s101, 0
	s_cmpk_gt_i32 s0, 0x3fff
	s_cbranch_scc1 .Lxo_nonext1
	global_load_dwordx2 v[80:81], v145, s[16:17]
	global_load_dwordx2 v[82:83], v145, s[18:19]
	global_load_dwordx2 v[48:49], v146, s[24:25] nt
	global_load_dwordx2 v[50:51], v146, s[24:25] offset:512 nt
	global_load_dwordx2 v[52:53], v146, s[24:25] offset:1024 nt
	global_load_dwordx2 v[54:55], v146, s[24:25] offset:1536 nt
	global_load_dwordx4 v[16:19], v144, s[20:21] nt
	global_load_dwordx4 v[20:23], v144, s[20:21] offset:1024 nt
	global_load_dwordx4 v[24:27], v144, s[20:21] offset:2048 nt
	global_load_dwordx4 v[28:31], v144, s[20:21] offset:3072 nt
	global_load_dwordx2 v[64:65], v146, s[26:27] nt
	global_load_dwordx2 v[66:67], v146, s[26:27] offset:512 nt
	global_load_dwordx2 v[68:69], v146, s[26:27] offset:1024 nt
	global_load_dwordx2 v[70:71], v146, s[26:27] offset:1536 nt
	global_load_dwordx2 v[56:57], v146, s[24:25] offset:2048 nt
	global_load_dwordx2 v[58:59], v146, s[24:25] offset:2560 nt
	global_load_dwordx2 v[60:61], v146, s[24:25] offset:3072 nt
	global_load_dwordx2 v[62:63], v146, s[24:25] offset:3584 nt
	global_load_dwordx4 v[32:35], v147, s[20:21] nt
	global_load_dwordx4 v[36:39], v147, s[20:21] offset:1024 nt
	global_load_dwordx4 v[40:43], v147, s[20:21] offset:2048 nt
	global_load_dwordx4 v[44:47], v147, s[20:21] offset:3072 nt
	global_load_dwordx2 v[72:73], v146, s[26:27] offset:2048 nt
	global_load_dwordx2 v[74:75], v146, s[26:27] offset:2560 nt
	global_load_dwordx2 v[76:77], v146, s[26:27] offset:3072 nt
	global_load_dwordx2 v[78:79], v146, s[26:27] offset:3584 nt
	s_add_i32 s0, s0, s4
	s_add_u32 s20, s20, s98
	s_addc_u32 s21, s21, 0
	s_add_u32 s24, s24, s99
	s_addc_u32 s25, s25, 0
	s_add_u32 s26, s26, s99
	s_addc_u32 s27, s27, 0
	s_add_u32 s16, s16, s100
	s_addc_u32 s17, s17, 0
	s_add_u32 s18, s18, s100
	s_addc_u32 s19, s19, 0
	s_mov_b32 s101, 1
	s_waitcnt vmcnt(38)
	s_branch .Lxo_rowA1

; __device__ __forceinline__ f32x4 up4(u32x2 w) { return (f32x4){bf_lo(w.x), bf_hi(w.x), bf_lo(w.y), bf_hi(w.y)}; }
; template <bool DRYR = false>
; __device__ __forceinline__ void row_pass2(const Args& a, int row_lo, int row_hi, int gw, int NGW, int lane) {
;     ...
;         for (int r = 0; r < 2; ++r) { const int row = r0 + r; if (row >= row_hi) break;
;             const float rstd = rsqrtf(rs[r] * (1.f / DM) + EPS); f32x4* xo = (f32x4*)(XO + (size_t)row * DM) + lane;
; #pragma unroll
;             for (int j = 0; j < 4; ++j) { const f32x4 o = xv[r][j] + up4(fv[r][j]) * rstd * gp[j]; if (!DRYR || o[0] == 123.456f) xo[64 * j] = o; } }
.Lxo_rowA1:
	v_fmamk_f32 v104, v180, 0x3a800000, v116
	v_mul_f32_e32 v105, 0x4b800000, v104
	v_cmp_gt_f32_e32 vcc, s3, v104
	s_nop 1
	v_cndmask_b32_e32 v104, v104, v105, vcc
	v_rsq_f32_e32 v104, v104
	s_nop 0
	v_mul_f32_e32 v105, 0x45800000, v104
	v_cndmask_b32_e32 v104, v104, v105, vcc
	v_fmamk_f32 v106, v182, 0x3a800000, v116
	v_mul_f32_e32 v107, 0x4b800000, v106
	v_cmp_gt_f32_e32 vcc, s3, v106
	s_nop 1
	v_cndmask_b32_e32 v106, v106, v107, vcc
	v_rsq_f32_e32 v106, v106
	s_nop 0
	v_mul_f32_e32 v107, 0x45800000, v106
	v_cndmask_b32_e32 v106, v106, v107, vcc
	v_lshlrev_b32_e32 v120, 16, v184
	v_and_b32_e32 v121, 0xffff0000, v184
	v_lshlrev_b32_e32 v122, 16, v185
	v_and_b32_e32 v123, 0xffff0000, v185
	v_lshlrev_b32_e32 v150, 16, v232
	v_and_b32_e32 v151, 0xffff0000, v232
	v_lshlrev_b32_e32 v152, 16, v233
	v_and_b32_e32 v153, 0xffff0000, v233
	v_pk_mul_f32 v[120:121], v[104:105], v[120:121] op_sel_hi:[0,1]
	v_pk_mul_f32 v[122:123], v[104:105], v[122:123] op_sel_hi:[0,1]
	v_pk_mul_f32 v[150:151], v[106:107], v[150:151] op_sel_hi:[0,1]
	v_pk_mul_f32 v[152:153], v[106:107], v[152:153] op_sel_hi:[0,1]
	v_pk_fma_f32 v[200:201], v[84:85], v[120:121], v[200:201]
	v_pk_fma_f32 v[202:203], v[86:87], v[122:123], v[202:203]
	v_pk_fma_f32 v[200:201], v[0:1], v[150:151], v[200:201]
	v_pk_fma_f32 v[202:203], v[2:3], v[152:153], v[202:203]
	v_lshlrev_b32_e32 v124, 16, v186
	v_and_b32_e32 v125, 0xffff0000, v186
	v_lshlrev_b32_e32 v126, 16, v187
	v_and_b32_e32 v127, 0xffff0000, v187
	v_lshlrev_b32_e32 v154, 16, v234
	v_and_b32_e32 v155, 0xffff0000, v234
	v_lshlrev_b32_e32 v156, 16, v235
	v_and_b32_e32 v157, 0xffff0000, v235
	v_pk_mul_f32 v[124:125], v[104:105], v[124:125] op_sel_hi:[0,1]
	v_pk_mul_f32 v[126:127], v[104:105], v[126:127] op_sel_hi:[0,1]
	v_pk_mul_f32 v[154:155], v[106:107], v[154:155] op_sel_hi:[0,1]
	v_pk_mul_f32 v[156:157], v[106:107], v[156:157] op_sel_hi:[0,1]
	v_pk_fma_f32 v[204:205], v[88:89], v[124:125], v[204:205]
	v_pk_fma_f32 v[206:207], v[90:91], v[126:127], v[206:207]
	v_pk_fma_f32 v[204:205], v[4:5], v[154:155], v[204:205]
	v_pk_fma_f32 v[206:207], v[6:7], v[156:157], v[206:207]
	v_lshlrev_b32_e32 v128, 16, v188
	v_and_b32_e32 v129, 0xffff0000, v188
	v_lshlrev_b32_e32 v130, 16, v189
	v_and_b32_e32 v131, 0xffff0000, v189
	v_lshlrev_b32_e32 v158, 16, v236
	v_and_b32_e32 v159, 0xffff0000, v236
	v_lshlrev_b32_e32 v160, 16, v237
	v_and_b32_e32 v161, 0xffff0000, v237
	v_pk_mul_f32 v[128:129], v[104:105], v[128:129] op_sel_hi:[0,1]
	v_pk_mul_f32 v[130:131], v[104:105], v[130:131] op_sel_hi:[0,1]
	v_pk_mul_f32 v[158:159], v[106:107], v[158:159] op_sel_hi:[0,1]
	v_pk_mul_f32 v[160:161], v[106:107], v[160:161] op_sel_hi:[0,1]
	v_pk_fma_f32 v[208:209], v[92:93], v[128:129], v[208:209]
	v_pk_fma_f32 v[210:211], v[94:95], v[130:131], v[210:211]
	v_pk_fma_f32 v[208:209], v[8:9], v[158:159], v[208:209]
	v_pk_fma_f32 v[210:211], v[10:11], v[160:161], v[210:211]
	v_lshlrev_b32_e32 v132, 16, v190
	v_and_b32_e32 v133, 0xffff0000, v190
	v_lshlrev_b32_e32 v134, 16, v191
	v_and_b32_e32 v135, 0xffff0000, v191
	v_lshlrev_b32_e32 v162, 16, v238
	v_and_b32_e32 v163, 0xffff0000, v238
	v_lshlrev_b32_e32 v164, 16, v239
	v_and_b32_e32 v165, 0xffff0000, v239
	v_pk_mul_f32 v[132:133], v[104:105], v[132:133] op_sel_hi:[0,1]
	v_pk_mul_f32 v[134:135], v[104:105], v[134:135] op_sel_hi:[0,1]
	v_pk_mul_f32 v[162:163], v[106:107], v[162:163] op_sel_hi:[0,1]
	v_pk_mul_f32 v[164:165], v[106:107], v[164:165] op_sel_hi:[0,1]
	v_pk_fma_f32 v[212:213], v[96:97], v[132:133], v[212:213]
	v_pk_fma_f32 v[214:215], v[98:99], v[134:135], v[214:215]
	v_pk_fma_f32 v[212:213], v[12:13], v[162:163], v[212:213]
	v_pk_fma_f32 v[214:215], v[14:15], v[164:165], v[214:215]
	global_store_dwordx4 v144, v[200:203], s[22:23] nt
	global_store_dwordx4 v144, v[204:207], s[22:23] offset:1024 nt
	global_store_dwordx4 v144, v[208:211], s[22:23] offset:2048 nt
	global_store_dwordx4 v144, v[212:215], s[22:23] offset:3072 nt
	s_cmp_lg_u32 s101, 0
	s_cbranch_scc1 .Lxo_wB1
	s_waitcnt vmcnt(4)
	s_branch .Lxo_rowB1

; __device__ __forceinline__ f32x4 up4(u32x2 w) { return (f32x4){bf_lo(w.x), bf_hi(w.x), bf_lo(w.y), bf_hi(w.y)}; }
; template <bool DRYR = false>
; __device__ __forceinline__ void row_pass2(const Args& a, int row_lo, int row_hi, int gw, int NGW, int lane) {
;     ...
;         for (int r = 0; r < 2; ++r) { const int row = r0 + r; if (row >= row_hi) break;
;             const float rstd = rsqrtf(rs[r] * (1.f / DM) + EPS); f32x4* xo = (f32x4*)(XO + (size_t)row * DM) + lane;
; #pragma unroll
;             for (int j = 0; j < 4; ++j) { const f32x4 o = xv[r][j] + up4(fv[r][j]) * rstd * gp[j]; if (!DRYR || o[0] == 123.456f) xo[64 * j] = o; } }
.Lxo_rowB1:
	v_fmamk_f32 v104, v181, 0x3a800000, v116
	v_mul_f32_e32 v105, 0x4b800000, v104
	v_cmp_gt_f32_e32 vcc, s3, v104
	s_nop 1
	v_cndmask_b32_e32 v104, v104, v105, vcc
	v_rsq_f32_e32 v104, v104
	s_nop 0
	v_mul_f32_e32 v105, 0x45800000, v104
	v_cndmask_b32_e32 v104, v104, v105, vcc
	v_fmamk_f32 v106, v183, 0x3a800000, v116
	v_mul_f32_e32 v107, 0x4b800000, v106
	v_cmp_gt_f32_e32 vcc, s3, v106
	s_nop 1
	v_cndmask_b32_e32 v106, v106, v107, vcc
	v_rsq_f32_e32 v106, v106
	s_nop 0
	v_mul_f32_e32 v107, 0x45800000, v106
	v_cndmask_b32_e32 v106, v106, v107, vcc
	v_lshlrev_b32_e32 v120, 16, v192
	v_and_b32_e32 v121, 0xffff0000, v192
	v_lshlrev_b32_e32 v122, 16, v193
	v_and_b32_e32 v123, 0xffff0000, v193
	v_lshlrev_b32_e32 v150, 16, v240
	v_and_b32_e32 v151, 0xffff0000, v240
	v_lshlrev_b32_e32 v152, 16, v241
	v_and_b32_e32 v153, 0xffff0000, v241
	v_pk_mul_f32 v[120:121], v[104:105], v[120:121] op_sel_hi:[0,1]
	v_pk_mul_f32 v[122:123], v[104:105], v[122:123] op_sel_hi:[0,1]
	v_pk_mul_f32 v[150:151], v[106:107], v[150:151] op_sel_hi:[0,1]
	v_pk_mul_f32 v[152:153], v[106:107], v[152:153] op_sel_hi:[0,1]
	v_pk_fma_f32 v[216:217], v[84:85], v[120:121], v[216:217]
	v_pk_fma_f32 v[218:219], v[86:87], v[122:123], v[218:219]
	v_pk_fma_f32 v[216:217], v[0:1], v[150:151], v[216:217]
	v_pk_fma_f32 v[218:219], v[2:3], v[152:153], v[218:219]
	v_lshlrev_b32_e32 v124, 16, v194
	v_and_b32_e32 v125, 0xffff0000, v194
	v_lshlrev_b32_e32 v126, 16, v195
	v_and_b32_e32 v127, 0xffff0000, v195
	v_lshlrev_b32_e32 v154, 16, v242
	v_and_b32_e32 v155, 0xffff0000, v242
	v_lshlrev_b32_e32 v156, 16, v243
	v_and_b32_e32 v157, 0xffff0000, v243
	v_pk_mul_f32 v[124:125], v[104:105], v[124:125] op_sel_hi:[0,1]
	v_pk_mul_f32 v[126:127], v[104:105], v[126:127] op_sel_hi:[0,1]
	v_pk_mul_f32 v[154:155], v[106:107], v[154:155] op_sel_hi:[0,1]
	v_pk_mul_f32 v[156:157], v[106:107], v[156:157] op_sel_hi:[0,1]
	v_pk_fma_f32 v[220:221], v[88:89], v[124:125], v[220:221]
	v_pk_fma_f32 v[222:223], v[90:91], v[126:127], v[222:223]
	v_pk_fma_f32 v[220:221], v[4:5], v[154:155], v[220:221]
	v_pk_fma_f32 v[222:223], v[6:7], v[156:157], v[222:223]
	v_lshlrev_b32_e32 v128, 16, v196
	v_and_b32_e32 v129, 0xffff0000, v196
	v_lshlrev_b32_e32 v130, 16, v197
	v_and_b32_e32 v131, 0xffff0000, v197
	v_lshlrev_b32_e32 v158, 16, v244
	v_and_b32_e32 v159, 0xffff0000, v244
	v_lshlrev_b32_e32 v160, 16, v245
	v_and_b32_e32 v161, 0xffff0000, v245
	v_pk_mul_f32 v[128:129], v[104:105], v[128:129] op_sel_hi:[0,1]
	v_pk_mul_f32 v[130:131], v[104:105], v[130:131] op_sel_hi:[0,1]
	v_pk_mul_f32 v[158:159], v[106:107], v[158:159] op_sel_hi:[0,1]
	v_pk_mul_f32 v[160:161], v[106:107], v[160:161] op_sel_hi:[0,1]
	v_pk_fma_f32 v[224:225], v[92:93], v[128:129], v[224:225]
	v_pk_fma_f32 v[226:227], v[94:95], v[130:131], v[226:227]
	v_pk_fma_f32 v[224:225], v[8:9], v[158:159], v[224:225]
	v_pk_fma_f32 v[226:227], v[10:11], v[160:161], v[226:227]
	v_lshlrev_b32_e32 v132, 16, v198
	v_and_b32_e32 v133, 0xffff0000, v198
	v_lshlrev_b32_e32 v134, 16, v199
	v_and_b32_e32 v135, 0xffff0000, v199
	v_lshlrev_b32_e32 v162, 16, v246
	v_and_b32_e32 v163, 0xffff0000, v246
	v_lshlrev_b32_e32 v164, 16, v247
	v_and_b32_e32 v165, 0xffff0000, v247
	v_pk_mul_f32 v[132:133], v[104:105], v[132:133] op_sel_hi:[0,1]
	v_pk_mul_f32 v[134:135], v[104:105], v[134:135] op_sel_hi:[0,1]
	v_pk_mul_f32 v[162:163], v[106:107], v[162:163] op_sel_hi:[0,1]
	v_pk_mul_f32 v[164:165], v[106:107], v[164:165] op_sel_hi:[0,1]
	v_pk_fma_f32 v[228:229], v[96:97], v[132:133], v[228:229]
	v_pk_fma_f32 v[230:231], v[98:99], v[134:135], v[230:231]
	v_pk_fma_f32 v[228:229], v[12:13], v[162:163], v[228:229]
	v_pk_fma_f32 v[230:231], v[14:15], v[164:165], v[230:231]
	global_store_dwordx4 v147, v[216:219], s[22:23] nt
	global_store_dwordx4 v147, v[220:223], s[22:23] offset:1024 nt
	global_store_dwordx4 v147, v[224:227], s[22:23] offset:2048 nt
	global_store_dwordx4 v147, v[228:231], s[22:23] offset:3072 nt
	s_add_u32 s22, s22, s98
	s_addc_u32 s23, s23, 0
	s_cmp_lg_u32 s101, 0
	s_cbranch_scc0 .Lxo_done
	s_branch .Lxo_half0
.Lxo_done:
.LBB0_1419:
	s_mov_b64 s[8:9], 0
